# speed-ranked tail also for the L1 input-projection GEMM (192-tile 7th round goes to the six fastest bid%8 groups), on keep_v8
# baseline (speedup 1.0000x reference)
.LBB0_176:
	v_and_b32_e32 v17, 15, v0
	v_bfe_u32 v0, v0, 4, 2
	v_lshlrev_b32_e32 v18, 4, v0
	s_add_u32 s60, s14, 0xac00000
	v_lshl_or_b32 v188, s2, 6, v17
	v_lshl_or_b32 v18, v17, 6, v18
	v_lshlrev_b32_e32 v17, 2, v17
	s_addc_u32 s61, s15, 0
	s_and_b32 s22, s3, 3
	s_lshl_b32 s2, s2, 13
	v_and_b32_e32 v19, 32, v17
	s_add_i32 m0, s40, 0x18000
	v_lshl_add_u64 v[8:9], v[8:9], 0, s[70:71]
	v_bitop3_b32 v20, v18, s2, v19 bitop3:0xde
	s_lshl_b32 s2, s22, 12
	s_waitcnt vmcnt(2)
	s_barrier
	global_load_lds_dwordx4 v[8:9], off
	v_lshl_add_u64 v[6:7], v[6:7], 0, s[70:71]
	s_add_i32 m0, s40, 0x1a000
	s_add_i32 s44, s40, 0x8000
	s_add_i32 s45, s40, 0xa000
	v_bitop3_b32 v189, s2, v18, v19 bitop3:0xf6
	global_load_lds_dwordx4 v[6:7], off
	v_lshl_add_u64 v[2:3], v[2:3], 0, s[70:71]
	s_mov_b32 m0, s44
	s_add_u32 s2, s6, 0x40080
	global_load_lds_dwordx4 v[2:3], off
	v_lshl_add_u64 v[2:3], v[4:5], 0, s[70:71]
	s_mov_b32 m0, s45
	s_addc_u32 s3, s7, 0
	global_load_lds_dwordx4 v[2:3], off
	s_add_i32 m0, s40, 0x1c000
	v_lshl_add_u64 v[2:3], s[2:3], 0, v[142:143]
	global_load_lds_dwordx4 v[2:3], off
	v_lshl_add_u64 v[2:3], s[2:3], 0, v[138:139]
	s_add_i32 m0, s40, 0x1e000
	v_lshlrev_b32_e32 v16, 3, v0
	global_load_lds_dwordx4 v[2:3], off
	v_lshlrev_b32_e32 v2, 6, v0
	s_movk_i32 s2, 0x80
	v_lshlrev_b32_e32 v0, 5, v0
	v_bitop3_b32 v190, v2, 64, v17 bitop3:0x36
	v_bitop3_b32 v191, v2, s2, v17 bitop3:0x36
	v_lshl_add_u64 v[2:3], s[14:15], 0, v[0:1]
	s_mov_b64 s[2:3], 0x200000
	v_lshlrev_b32_e32 v0, 14, v14
	v_lshl_add_u64 v[146:147], v[2:3], 0, s[2:3]
	s_mov_b64 s[2:3], 0x240000
	v_and_b32_e32 v0, 0xffff8000, v0
	v_lshl_add_u64 v[156:157], v[2:3], 0, s[2:3]
	v_lshl_add_u32 v0, v13, 11, v0
	v_and_b32_e32 v2, 1, v14
	v_lshl_or_b32 v0, v2, 6, v0
	v_lshl_add_u32 v158, v15, 1, v0
	v_lshlrev_b32_e32 v0, 14, v10
	v_and_b32_e32 v0, 0xffff8000, v0
	s_waitcnt vmcnt(6)
	v_lshl_add_u32 v0, v11, 11, v0
	v_and_b32_e32 v2, 1, v10
	s_cmpk_lt_u32 s9, 0x100
	v_lshl_or_b32 v0, v2, 6, v0
	v_readlane_b32 s2, v255, 39
	s_cselect_b64 s[36:37], -1, 0
	v_lshl_or_b32 v192, s22, 6, v16
	v_mov_b32_e32 v159, v1
	v_lshl_add_u32 v160, v12, 1, v0
	v_mov_b32_e32 v161, v1
	s_mov_b32 s46, 0
	v_add_u32_e32 v193, 0, v20
	v_lshlrev_b32_e32 v194, 2, v16
	v_readlane_b32 s48, v255, 15
	s_mov_b32 s47, s2
	s_barrier
	v_readlane_b32 s3, v255, 40
	s_mov_b32 s100, 0x10000
	s_cmpk_lg_u32 s33, 0x100
	s_cbranch_scc1 .Lt1_slot_done
	s_load_dwordx2 s[98:99], s[0:1], 0x128
	s_and_b32 s101, s8, 7
	s_lshl_b32 s101, s101, 8
	s_waitcnt lgkmcnt(0)
	s_add_u32 s98, s98, s101
	s_addc_u32 s99, s99, 0
	s_add_u32 s98, s98, 0x302400
	s_addc_u32 s99, s99, 0
	global_load_dword v2, v1, s[98:99] sc1
	s_waitcnt vmcnt(0)
	v_readfirstlane_b32 s101, v2
	s_nop 3
	s_cmp_lt_u32 s101, 6
	s_cbranch_scc0 .Lt1_slot_done
	s_lshl_b32 s101, s101, 5
	s_lshr_b32 s100, s8, 3
	s_add_i32 s100, s100, s101
.Lt1_slot_done:
	s_branch .LBB0_179
.LBB0_177:
	s_mov_b64 s[2:3], 0

.LBB0_179:
	s_add_i32 s46, s46, 1
	s_mul_i32 s2, s46, s34
	s_mul_hi_u32 s3, s46, s33
	s_add_i32 s3, s3, s2
	s_mul_i32 s2, s46, s33
	s_add_u32 s22, s2, s8
	s_addc_u32 s23, s3, s55
	s_cmp_lg_u32 s46, 6
	s_cbranch_scc1 .Lt1_done
	s_cmpk_lg_u32 s33, 0x100
	s_cbranch_scc1 .Lt1_done
	s_add_i32 s22, s100, 0x600
	s_mov_b32 s23, 0
.Lt1_done:
	v_mov_b64_e32 v[2:3], 0x6c0
	v_cmp_lt_i64_e64 s[2:3], s[22:23], v[2:3]
	v_mov_b64_e32 v[2:3], 0x6bf
	v_cmp_gt_i64_e32 vcc, s[22:23], v[2:3]
	s_cbranch_vccnz .LBB0_181
	s_ashr_i32 s9, s22, 31
	s_lshr_b32 s9, s9, 29
	s_add_i32 s9, s22, s9
	s_ashr_i32 s14, s9, 3
	s_and_b32 s9, s9, -8
	s_sub_i32 s9, s22, s9
	s_cmp_lt_i32 s9, 0
	s_movk_i32 s15, 0xd9
	s_cselect_b32 s15, s15, 0xd8
	s_mul_i32 s9, s9, s15
	s_add_i32 s9, s9, s14
	s_mul_hi_i32 s14, s9, 0x2aaaaaab
	s_lshr_b32 s15, s14, 31
	s_ashr_i32 s14, s14, 4
	s_add_i32 s14, s14, s15
	s_lshl_b32 s15, s14, 3
	s_sub_i32 s22, 0x90, s15
	s_min_i32 s22, s22, 8
	s_abs_i32 s23, s22
	v_cvt_f32_u32_e32 v0, s23
	s_sub_i32 s25, 0, s23
	s_mulk_i32 s14, 0x60
	s_sub_i32 s9, s9, s14
	v_rcp_iflag_f32_e32 v0, v0
	s_abs_i32 s14, s9
	s_xor_b32 s24, s9, s22
	s_ashr_i32 s24, s24, 31
	v_mul_f32_e32 v0, 0x4f7ffffe, v0
	v_cvt_u32_f32_e32 v0, v0
	s_nop 0
	v_readfirstlane_b32 s26, v0
	s_mul_i32 s25, s25, s26
	s_mul_hi_u32 s25, s26, s25
	s_add_i32 s26, s26, s25
	s_mul_hi_u32 s25, s14, s26
	s_mul_i32 s26, s25, s23
	s_sub_i32 s14, s14, s26
	s_add_i32 s27, s25, 1
	s_sub_i32 s26, s14, s23
	s_cmp_ge_u32 s14, s23
	s_cselect_b32 s25, s27, s25
	s_cselect_b32 s14, s26, s14
	s_add_i32 s26, s25, 1
	s_cmp_ge_u32 s14, s23
	s_cselect_b32 s14, s26, s25
	s_xor_b32 s14, s14, s24
	s_sub_i32 s14, s14, s24
	s_mul_i32 s22, s14, s22
	s_sub_i32 s9, s9, s22
	s_add_i32 s38, s15, s9
